# v011 + accumulator zeroing with v_mov_b64 (64 instead of 127 movs per GEMM unit, all 4 loops)
# speedup vs baseline: 1.0111x; 1.0063x over previous
.LBB0_124:
	s_ashr_i32 s79, s78, 31
	s_lshl_b64 s[10:11], s[78:79], 19
	s_add_u32 s80, s54, s10
	v_cmp_lt_i64_e32 vcc, s[72:73], v[178:179]
	s_addc_u32 s81, s55, s11
	s_and_b64 s[10:11], vcc, exec
	s_cselect_b32 s1, s81, s87
	s_cselect_b32 s10, s80, s86
	s_ashr_i32 s77, s76, 31
	s_lshl_b64 s[36:37], s[76:77], 19
	s_add_u32 s72, s66, s36
	s_addc_u32 s73, s59, s37
	s_and_b64 s[36:37], vcc, exec
	s_cselect_b32 s11, s73, s83
	s_cselect_b32 s25, s72, s82
	s_add_u32 s86, s86, 0x40080
	s_addc_u32 s87, s87, 0
	s_add_u32 s33, s82, 0x100
	v_mov_b32_e32 v0, 0
	s_addc_u32 s36, s83, 0
	s_mov_b32 s37, -2
	v_mov_b32_e32 v1, 0
	v_mov_b64_e32 v[2:3], 0
	v_mov_b64_e32 v[4:5], 0
	v_mov_b64_e32 v[6:7], 0
	v_mov_b64_e32 v[8:9], 0
	v_mov_b64_e32 v[10:11], 0
	v_mov_b64_e32 v[12:13], 0
	v_mov_b64_e32 v[14:15], 0
	v_mov_b64_e32 v[16:17], 0
	v_mov_b64_e32 v[18:19], 0
	v_mov_b64_e32 v[20:21], 0
	v_mov_b64_e32 v[22:23], 0
	v_mov_b64_e32 v[24:25], 0
	v_mov_b64_e32 v[26:27], 0
	v_mov_b64_e32 v[28:29], 0
	v_mov_b64_e32 v[30:31], 0
	v_mov_b64_e32 v[32:33], 0
	v_mov_b64_e32 v[34:35], 0
	v_mov_b64_e32 v[36:37], 0
	v_mov_b64_e32 v[38:39], 0
	v_mov_b64_e32 v[40:41], 0
	v_mov_b64_e32 v[42:43], 0
	v_mov_b64_e32 v[44:45], 0
	v_mov_b64_e32 v[46:47], 0
	v_mov_b64_e32 v[48:49], 0
	v_mov_b64_e32 v[50:51], 0
	v_mov_b64_e32 v[52:53], 0
	v_mov_b64_e32 v[54:55], 0
	v_mov_b64_e32 v[56:57], 0
	v_mov_b64_e32 v[58:59], 0
	v_mov_b64_e32 v[60:61], 0
	v_mov_b64_e32 v[62:63], 0
	v_mov_b64_e32 v[96:97], 0
	v_mov_b64_e32 v[98:99], 0
	v_mov_b64_e32 v[100:101], 0
	v_mov_b64_e32 v[102:103], 0
	v_mov_b64_e32 v[104:105], 0
	v_mov_b64_e32 v[106:107], 0
	v_mov_b64_e32 v[108:109], 0
	v_mov_b64_e32 v[110:111], 0
	v_mov_b64_e32 v[112:113], 0
	v_mov_b64_e32 v[114:115], 0
	v_mov_b64_e32 v[116:117], 0
	v_mov_b64_e32 v[118:119], 0
	v_mov_b64_e32 v[120:121], 0
	v_mov_b64_e32 v[122:123], 0
	v_mov_b64_e32 v[124:125], 0
	v_mov_b64_e32 v[126:127], 0
	v_mov_b64_e32 v[128:129], 0
	v_mov_b64_e32 v[130:131], 0
	v_mov_b64_e32 v[132:133], 0
	v_mov_b64_e32 v[134:135], 0
	v_mov_b64_e32 v[136:137], 0
	v_mov_b64_e32 v[138:139], 0
	v_mov_b64_e32 v[140:141], 0
	v_mov_b64_e32 v[142:143], 0
	v_mov_b64_e32 v[146:147], 0
	v_mov_b64_e32 v[148:149], 0
	v_mov_b64_e32 v[150:151], 0
	v_mov_b64_e32 v[152:153], 0
	v_mov_b64_e32 v[154:155], 0
	v_mov_b64_e32 v[156:157], 0
	v_mov_b64_e32 v[158:159], 0
	v_mov_b64_e32 v[160:161], 0

.LBB0_195:
	s_add_u32 s42, s78, 0x80
	s_addc_u32 s43, s79, 0
	s_add_u32 s33, s44, 0x100
	v_mov_b32_e32 v0, 0
	s_addc_u32 s37, s45, 0
	s_mov_b32 s27, 0
	s_waitcnt lgkmcnt(0)
	v_mov_b32_e32 v1, 0
	v_mov_b64_e32 v[2:3], 0
	v_mov_b64_e32 v[4:5], 0
	v_mov_b64_e32 v[6:7], 0
	v_mov_b64_e32 v[8:9], 0
	v_mov_b64_e32 v[10:11], 0
	v_mov_b64_e32 v[12:13], 0
	v_mov_b64_e32 v[14:15], 0
	v_mov_b64_e32 v[16:17], 0
	v_mov_b64_e32 v[18:19], 0
	v_mov_b64_e32 v[20:21], 0
	v_mov_b64_e32 v[22:23], 0
	v_mov_b64_e32 v[24:25], 0
	v_mov_b64_e32 v[26:27], 0
	v_mov_b64_e32 v[28:29], 0
	v_mov_b64_e32 v[30:31], 0
	v_mov_b64_e32 v[32:33], 0
	v_mov_b64_e32 v[34:35], 0
	v_mov_b64_e32 v[36:37], 0
	v_mov_b64_e32 v[38:39], 0
	v_mov_b64_e32 v[40:41], 0
	v_mov_b64_e32 v[42:43], 0
	v_mov_b64_e32 v[44:45], 0
	v_mov_b64_e32 v[46:47], 0
	v_mov_b64_e32 v[48:49], 0
	v_mov_b64_e32 v[50:51], 0
	v_mov_b64_e32 v[52:53], 0
	v_mov_b64_e32 v[54:55], 0
	v_mov_b64_e32 v[56:57], 0
	v_mov_b64_e32 v[58:59], 0
	v_mov_b64_e32 v[60:61], 0
	v_mov_b64_e32 v[62:63], 0
	v_mov_b64_e32 v[64:65], 0
	v_mov_b64_e32 v[66:67], 0
	v_mov_b64_e32 v[68:69], 0
	v_mov_b64_e32 v[70:71], 0
	v_mov_b64_e32 v[72:73], 0
	v_mov_b64_e32 v[74:75], 0
	v_mov_b64_e32 v[76:77], 0
	v_mov_b64_e32 v[78:79], 0
	v_mov_b64_e32 v[80:81], 0
	v_mov_b64_e32 v[82:83], 0
	v_mov_b64_e32 v[84:85], 0
	v_mov_b64_e32 v[86:87], 0
	v_mov_b64_e32 v[88:89], 0
	v_mov_b64_e32 v[90:91], 0
	v_mov_b64_e32 v[92:93], 0
	v_mov_b64_e32 v[94:95], 0
	v_mov_b64_e32 v[96:97], 0
	v_mov_b64_e32 v[98:99], 0
	v_mov_b64_e32 v[100:101], 0
	v_mov_b64_e32 v[102:103], 0
	v_mov_b64_e32 v[104:105], 0
	v_mov_b64_e32 v[106:107], 0
	v_mov_b64_e32 v[108:109], 0
	v_mov_b64_e32 v[110:111], 0
	v_mov_b64_e32 v[112:113], 0
	v_mov_b64_e32 v[114:115], 0
	v_mov_b64_e32 v[116:117], 0
	v_mov_b64_e32 v[118:119], 0
	v_mov_b64_e32 v[120:121], 0
	v_mov_b64_e32 v[122:123], 0
	v_mov_b64_e32 v[124:125], 0
	v_mov_b64_e32 v[126:127], 0

.LBB0_325:
	s_ashr_i32 s93, s92, 31
	s_lshl_b64 s[30:31], s[92:93], 19
	s_add_u32 s94, s54, s30
	v_cmp_lt_i64_e32 vcc, s[50:51], v[186:187]
	s_addc_u32 s95, s55, s31
	s_and_b64 s[30:31], vcc, exec
	s_cselect_b32 s1, s95, s53
	s_cselect_b32 s11, s94, s52
	s_ashr_i32 s9, s8, 31
	s_lshl_b64 s[30:31], s[8:9], 19
	s_add_u32 s28, s80, s30
	s_addc_u32 s29, s78, s31
	s_and_b64 s[30:31], vcc, exec
	s_cselect_b32 s25, s29, s73
	s_cselect_b32 s30, s28, s72
	s_add_u32 s52, s52, 0x40080
	s_addc_u32 s53, s53, 0
	s_add_u32 s31, s72, 0x100
	v_mov_b32_e32 v0, 0
	s_addc_u32 s33, s73, 0
	s_mov_b32 s34, -2
	v_mov_b32_e32 v1, 0
	v_mov_b64_e32 v[2:3], 0
	v_mov_b64_e32 v[4:5], 0
	v_mov_b64_e32 v[6:7], 0
	v_mov_b64_e32 v[8:9], 0
	v_mov_b64_e32 v[10:11], 0
	v_mov_b64_e32 v[12:13], 0
	v_mov_b64_e32 v[14:15], 0
	v_mov_b64_e32 v[16:17], 0
	v_mov_b64_e32 v[18:19], 0
	v_mov_b64_e32 v[20:21], 0
	v_mov_b64_e32 v[22:23], 0
	v_mov_b64_e32 v[24:25], 0
	v_mov_b64_e32 v[26:27], 0
	v_mov_b64_e32 v[28:29], 0
	v_mov_b64_e32 v[30:31], 0
	v_mov_b64_e32 v[32:33], 0
	v_mov_b64_e32 v[34:35], 0
	v_mov_b64_e32 v[36:37], 0
	v_mov_b64_e32 v[38:39], 0
	v_mov_b64_e32 v[40:41], 0
	v_mov_b64_e32 v[42:43], 0
	v_mov_b64_e32 v[44:45], 0
	v_mov_b64_e32 v[46:47], 0
	v_mov_b64_e32 v[48:49], 0
	v_mov_b64_e32 v[50:51], 0
	v_mov_b64_e32 v[52:53], 0
	v_mov_b64_e32 v[54:55], 0
	v_mov_b64_e32 v[56:57], 0
	v_mov_b64_e32 v[58:59], 0
	v_mov_b64_e32 v[60:61], 0
	v_mov_b64_e32 v[62:63], 0
	v_mov_b64_e32 v[64:65], 0
	v_mov_b64_e32 v[66:67], 0
	v_mov_b64_e32 v[68:69], 0
	v_mov_b64_e32 v[70:71], 0
	v_mov_b64_e32 v[72:73], 0
	v_mov_b64_e32 v[74:75], 0
	v_mov_b64_e32 v[76:77], 0
	v_mov_b64_e32 v[78:79], 0
	v_mov_b64_e32 v[80:81], 0
	v_mov_b64_e32 v[82:83], 0
	v_mov_b64_e32 v[84:85], 0
	v_mov_b64_e32 v[86:87], 0
	v_mov_b64_e32 v[88:89], 0
	v_mov_b64_e32 v[90:91], 0
	v_mov_b64_e32 v[92:93], 0
	v_mov_b64_e32 v[94:95], 0
	v_mov_b64_e32 v[96:97], 0
	v_mov_b64_e32 v[98:99], 0
	v_mov_b64_e32 v[100:101], 0
	v_mov_b64_e32 v[102:103], 0
	v_mov_b64_e32 v[104:105], 0
	v_mov_b64_e32 v[106:107], 0
	v_mov_b64_e32 v[108:109], 0
	v_mov_b64_e32 v[110:111], 0
	v_mov_b64_e32 v[112:113], 0
	v_mov_b64_e32 v[114:115], 0
	v_mov_b64_e32 v[116:117], 0
	v_mov_b64_e32 v[118:119], 0
	v_mov_b64_e32 v[120:121], 0
	v_mov_b64_e32 v[122:123], 0
	v_mov_b64_e32 v[124:125], 0
	v_mov_b64_e32 v[126:127], 0

.LBB0_350:
	s_lshl_b32 s25, s84, 1
	s_add_i32 s25, s85, s25
	s_and_b32 s85, s25, 3
	s_lshl_b32 s25, s85, 19
	s_add_u32 s92, s74, s25
	v_cmp_lt_i64_e32 vcc, s[52:53], v[180:181]
	s_addc_u32 s93, s75, 0
	s_and_b64 s[30:31], vcc, exec
	s_cselect_b32 s25, s93, s1
	s_cselect_b32 s30, s92, s0
	s_ashr_i32 s47, s46, 31
	s_lshl_b64 s[34:35], s[46:47], 19
	s_add_u32 s94, s54, s34
	s_addc_u32 s95, s55, s35
	s_and_b64 s[34:35], vcc, exec
	s_cselect_b32 s31, s95, s51
	s_cselect_b32 s33, s94, s50
	s_add_u32 s0, s0, 0x40080
	s_addc_u32 s1, s1, 0
	s_add_u32 s34, s50, 0x100
	v_mov_b32_e32 v0, 0
	s_addc_u32 s35, s51, 0
	s_mov_b32 s36, -2
	v_mov_b32_e32 v1, 0
	v_mov_b64_e32 v[2:3], 0
	v_mov_b64_e32 v[4:5], 0
	v_mov_b64_e32 v[6:7], 0
	v_mov_b64_e32 v[8:9], 0
	v_mov_b64_e32 v[10:11], 0
	v_mov_b64_e32 v[12:13], 0
	v_mov_b64_e32 v[14:15], 0
	v_mov_b64_e32 v[16:17], 0
	v_mov_b64_e32 v[18:19], 0
	v_mov_b64_e32 v[20:21], 0
	v_mov_b64_e32 v[22:23], 0
	v_mov_b64_e32 v[24:25], 0
	v_mov_b64_e32 v[26:27], 0
	v_mov_b64_e32 v[28:29], 0
	v_mov_b64_e32 v[30:31], 0
	v_mov_b64_e32 v[32:33], 0
	v_mov_b64_e32 v[34:35], 0
	v_mov_b64_e32 v[36:37], 0
	v_mov_b64_e32 v[38:39], 0
	v_mov_b64_e32 v[40:41], 0
	v_mov_b64_e32 v[42:43], 0
	v_mov_b64_e32 v[44:45], 0
	v_mov_b64_e32 v[46:47], 0
	v_mov_b64_e32 v[48:49], 0
	v_mov_b64_e32 v[50:51], 0
	v_mov_b64_e32 v[52:53], 0
	v_mov_b64_e32 v[54:55], 0
	v_mov_b64_e32 v[56:57], 0
	v_mov_b64_e32 v[58:59], 0
	v_mov_b64_e32 v[60:61], 0
	v_mov_b64_e32 v[62:63], 0
	v_mov_b64_e32 v[64:65], 0
	v_mov_b64_e32 v[66:67], 0
	v_mov_b64_e32 v[68:69], 0
	v_mov_b64_e32 v[70:71], 0
	v_mov_b64_e32 v[72:73], 0
	v_mov_b64_e32 v[74:75], 0
	v_mov_b64_e32 v[76:77], 0
	v_mov_b64_e32 v[78:79], 0
	v_mov_b64_e32 v[80:81], 0
	v_mov_b64_e32 v[82:83], 0
	v_mov_b64_e32 v[84:85], 0
	v_mov_b64_e32 v[86:87], 0
	v_mov_b64_e32 v[88:89], 0
	v_mov_b64_e32 v[90:91], 0
	v_mov_b64_e32 v[92:93], 0
	v_mov_b64_e32 v[94:95], 0
	v_mov_b64_e32 v[96:97], 0
	v_mov_b64_e32 v[98:99], 0
	v_mov_b64_e32 v[100:101], 0
	v_mov_b64_e32 v[102:103], 0
	v_mov_b64_e32 v[104:105], 0
	v_mov_b64_e32 v[106:107], 0
	v_mov_b64_e32 v[108:109], 0
	v_mov_b64_e32 v[110:111], 0
	v_mov_b64_e32 v[112:113], 0
	v_mov_b64_e32 v[114:115], 0
	v_mov_b64_e32 v[116:117], 0
	v_mov_b64_e32 v[118:119], 0
	v_mov_b64_e32 v[120:121], 0
	v_mov_b64_e32 v[122:123], 0
	v_mov_b64_e32 v[124:125], 0
	v_mov_b64_e32 v[126:127], 0
